# diff-attention block B: row-max chain moved into the PV MFMA gaps and the cross-half bpermute issued before the QK chain (latency hidden)
# speedup vs baseline: 1.0041x; 1.0041x over previous
.LBB0_512:
	s_and_b32 s20, s2, 0xc000
	s_add_i32 s20, s65, s20
	v_mfma_f32_32x32x16_bf16 v[0:15], v[156:159], v[196:199], v[0:15]
	ds_read_b64_tr_b16 v[128:129], v238 offset:2048
	ds_read_b64_tr_b16 v[130:131], v238 offset:2560
	v_exp_f32_e32 v160, v96
	v_exp_f32_e32 v161, v97
	v_max3_f32 v241, v96, v97, v98
	v_add_u32_e32 v152, s20, v228
	v_add_u32_e32 v239, s20, v229
	v_add_u32_e32 v240, s20, v230
	v_mfma_f32_32x32x16_bf16 v[0:15], v[162:165], v[192:195], v[0:15]
	ds_read_b64_tr_b16 v[132:133], v238 offset:3072
	ds_read_b64_tr_b16 v[134:135], v238 offset:3584
	v_exp_f32_e32 v166, v98
	v_exp_f32_e32 v167, v99
	v_max3_f32 v242, v99, v100, v101
	v_mfma_f32_32x32x16_bf16 v[32:47], v[156:159], v[188:191], v[32:47]
	ds_read_b64_tr_b16 v[136:137], v238 offset:6144
	ds_read_b64_tr_b16 v[138:139], v238 offset:6656
	v_exp_f32_e32 v192, v100
	v_exp_f32_e32 v193, v101
	v_max3_f32 v241, v241, v102, v103
	v_mfma_f32_32x32x16_bf16 v[32:47], v[162:165], v[184:187], v[32:47]
	ds_read_b64_tr_b16 v[140:141], v238 offset:7168
	ds_read_b64_tr_b16 v[142:143], v238 offset:7680
	v_exp_f32_e32 v188, v102
	v_exp_f32_e32 v189, v103
	v_max3_f32 v242, v242, v104, v105
	v_mfma_f32_32x32x16_bf16 v[48:63], v[156:159], v[180:183], v[48:63]
	ds_read_b64_tr_b16 v[144:145], v238 offset:10240
	ds_read_b64_tr_b16 v[146:147], v238 offset:10752
	v_exp_f32_e32 v184, v104
	v_exp_f32_e32 v185, v105
	v_max3_f32 v241, v241, v106, v107
	v_mfma_f32_32x32x16_bf16 v[48:63], v[162:165], v[176:179], v[48:63]
	ds_read_b64_tr_b16 v[148:149], v238 offset:11264
	ds_read_b64_tr_b16 v[150:151], v238 offset:11776
	ds_read_b128 v[180:183], v152
	v_exp_f32_e32 v186, v106
	v_exp_f32_e32 v187, v107
	v_max3_f32 v242, v242, v108, v109
	v_mfma_f32_32x32x16_bf16 v[16:31], v[156:159], v[172:175], v[16:31]
	ds_read_b64_tr_b16 v[152:153], v238 offset:14336
	ds_read_b64_tr_b16 v[154:155], v238 offset:14848
	v_exp_f32_e32 v176, v108
	v_exp_f32_e32 v177, v109
	v_max3_f32 v241, v241, v110, v111
	v_mfma_f32_32x32x16_bf16 v[16:31], v[162:165], v[168:171], v[16:31]
	ds_read_b64_tr_b16 v[156:157], v238 offset:15360
	ds_read_b64_tr_b16 v[158:159], v238 offset:15872
	v_add_f32_e32 v162, v166, v160
	v_add_f32_e32 v163, v167, v161
	v_exp_f32_e32 v178, v110
	v_exp_f32_e32 v179, v111
	v_max_f32_e32 v243, v241, v242
	ds_bpermute_b32 v244, v214, v243
	v_pk_add_f32 v[164:165], v[192:193], v[162:163]
	ds_read_b128 v[168:171], v239
	ds_read_b128 v[172:175], v240
	v_pk_add_f32 v[164:165], v[188:189], v[164:165]
	v_cvt_pk_bf16_f32 v160, v160, v161
	v_cvt_pk_bf16_f32 v161, v166, v167
	v_pk_add_f32 v[166:167], v[184:185], v[164:165]
	v_cvt_pk_bf16_f32 v162, v192, v193
	v_pk_add_f32 v[166:167], v[186:187], v[166:167]
	v_cvt_pk_bf16_f32 v163, v188, v189
	v_cvt_pk_bf16_f32 v164, v184, v185
	v_cvt_pk_bf16_f32 v165, v186, v187
	v_pk_add_f32 v[184:185], v[176:177], v[166:167]
	v_cvt_pk_bf16_f32 v166, v176, v177
	v_cvt_pk_bf16_f32 v167, v178, v179
	v_pk_add_f32 v[176:177], v[178:179], v[184:185]
	s_waitcnt lgkmcnt(7)
	v_mfma_f32_32x32x16_bf16 v[80:95], v[180:183], v[112:115], v[64:79]
	v_add_f32_e32 v96, v176, v177
	v_add_f32_e32 v235, v235, v96
	v_add_u32_e32 v96, s20, v231
	ds_read_b128 v[96:99], v96
	s_waitcnt lgkmcnt(2)
	v_mfma_f32_32x32x16_bf16 v[80:95], v[168:171], v[116:119], v[80:95]
	s_waitcnt lgkmcnt(1)
	v_mfma_f32_32x32x16_bf16 v[80:95], v[172:175], v[120:123], v[80:95]
	s_waitcnt lgkmcnt(0)
	v_mfma_f32_32x32x16_bf16 v[80:95], v[96:99], v[124:127], v[80:95]
	s_waitcnt lgkmcnt(0)
	v_max_f32_e32 v96, v243, v244
	s_addk_i32 s2, 0x4000
	s_add_i32 s3, s3, -1
	s_cmp_ge_u32 s37, s84
	s_cbranch_scc1 .LBB0_527
	s_mov_b32 s76, s37
	s_branch .LBB0_502
